# GQA fast path: second-half softmax finish (8 exps, sums, cvt, swaps) and its two staging loads moved from the QK gaps into the first PV gaps (QK phase was VALU-saturated, PV phase nearly empty)
# speedup vs baseline: 1.0018x; 1.0001x over previous
; __device__ __forceinline__ void finishSM(f32x16& p0, f32x16& p1, float alpha, float& l_reg, bf16x8& pa0, bf16x8& pa1, bf16x8& pa2, bf16x8& pa3) {
; #pragma unroll
;   for (int r = 0; r < 16; ++r) p1[r] = __builtin_amdgcn_exp2f(p1[r]);
;   float ps = 0;
; #pragma unroll
;   for (int r = 0; r < 16; ++r) ps += p0[r];
; #pragma unroll
;   for (int r = 0; r < 16; ++r) ps += p1[r];
;   { auto rr = __builtin_amdgcn_permlane32_swap(__float_as_uint(ps), __float_as_uint(ps), false, false);
;     ps = __uint_as_float(rr[0]) + __uint_as_float(rr[1]); }
;   l_reg = l_reg * alpha + ps;
;     ...
;   PK4(p0, 0, pa0); PK4(p0, 8, pa1); PK4(p1, 0, pa2); PK4(p1, 8, pa3);
;     ...
; }
; template <int DQK> __device__ __forceinline__ void qkt(f32x16& p0, f32x16& p1, const char* Ks, const bf16x8* qr, int r32, int hi, const f32x16& negm) {
; #pragma unroll
;   for (int d0 = 0; d0 < DQK / 16; ++d0) { const int cb = (d0 * 16 + hi * 8) * 2;
;     const bf16x8 b0 = *reinterpret_cast<const bf16x8*>(Ks + (DQK == 128 ? KSWZ(r32, cb) : KSWZ64(r32, cb)));
;     const bf16x8 b1 = *reinterpret_cast<const bf16x8*>(Ks + (DQK == 128 ? KSWZ(32 + r32, cb) : KSWZ64(32 + r32, cb)));
;     if (d0 == 0) { p0 = __builtin_amdgcn_mfma_f32_32x32x16_bf16(b0, qr[0], negm, 0, 0, 0); p1 = __builtin_amdgcn_mfma_f32_32x32x16_bf16(b1, qr[0], negm, 0, 0, 0); }
;     else { p0 = __builtin_amdgcn_mfma_f32_32x32x16_bf16(b0, qr[d0], p0, 0, 0, 0); p1 = __builtin_amdgcn_mfma_f32_32x32x16_bf16(b1, qr[d0], p1, 0, 0, 0); } }
; }
.LBB0_69:
	s_add_i32 s99, s12, 64
	s_cmp_le_u32 s99, s16
	s_cbranch_scc0 .Lslow_g1
	ds_read_b128 v[198:201], v195 offset:57344
	ds_read_b128 v[202:205], v195 offset:49152
	ds_read_b128 v[244:247], v211 offset:57344
	ds_read_b128 v[206:209], v211 offset:49152
	v_add_f32_e32 v227, 0, v238
	v_add_f32_e32 v227, v240, v227
	v_cvt_pk_bf16_f32 v66, v238, v240
	v_add_f32_e32 v227, v236, v227
	v_add_f32_e32 v227, v239, v227
	v_cvt_pk_bf16_f32 v67, v236, v239
	v_add_f32_e32 v227, v235, v227
	v_add_f32_e32 v227, v237, v227
	v_cvt_pk_bf16_f32 v68, v235, v237
	v_add_f32_e32 v227, v233, v227
	v_add_f32_e32 v227, v234, v227
	v_cvt_pk_bf16_f32 v69, v233, v234
	s_waitcnt lgkmcnt(3)
	v_mfma_f32_32x32x16_bf16 v[114:129], v[198:201], v[174:177], v[82:97]
	v_add_f32_e32 v227, v184, v227
	v_add_f32_e32 v227, v232, v227
	v_cvt_pk_bf16_f32 v70, v184, v232
	s_waitcnt lgkmcnt(2)
	v_mfma_f32_32x32x16_bf16 v[130:145], v[202:205], v[174:177], v[82:97]
	ds_read_b128 v[198:201], v210 offset:57344
	ds_read_b128 v[202:205], v210 offset:49152
	v_add_f32_e32 v227, v183, v227
	v_add_f32_e32 v227, v185, v227
	v_cvt_pk_bf16_f32 v71, v183, v185
	s_waitcnt lgkmcnt(3)
	v_mfma_f32_32x32x16_bf16 v[114:129], v[244:247], v[170:173], v[114:129]
	v_add_f32_e32 v227, v180, v227
	v_add_f32_e32 v227, v182, v227
	v_cvt_pk_bf16_f32 v72, v180, v182
	s_waitcnt lgkmcnt(2)
	v_mfma_f32_32x32x16_bf16 v[130:145], v[206:209], v[170:173], v[130:145]
	ds_read_b128 v[244:247], v197 offset:57344
	ds_read_b128 v[206:209], v197 offset:49152
	v_add_f32_e32 v227, v179, v227
	v_add_f32_e32 v227, v181, v227
	v_cvt_pk_bf16_f32 v73, v179, v181
	s_waitcnt lgkmcnt(3)
	v_mfma_f32_32x32x16_bf16 v[114:129], v[198:201], v[166:169], v[114:129]
	v_exp_f32_e32 v98, v98
	v_exp_f32_e32 v99, v99
	v_permlane32_swap_b32_e32 v66, v68
	s_waitcnt lgkmcnt(2)
	v_mfma_f32_32x32x16_bf16 v[130:145], v[202:205], v[166:169], v[130:145]
	ds_read_b128 v[198:201], v196 offset:57344
	ds_read_b128 v[202:205], v196 offset:49152
	v_permlane32_swap_b32_e32 v67, v69
	v_permlane32_swap_b32_e32 v70, v72
	v_permlane32_swap_b32_e32 v71, v73
	s_waitcnt lgkmcnt(3)
	v_mfma_f32_32x32x16_bf16 v[114:129], v[244:247], v[162:165], v[114:129]
	v_exp_f32_e32 v100, v100
	v_add_f32_e32 v227, v98, v227
	v_exp_f32_e32 v101, v101
	s_waitcnt lgkmcnt(2)
	v_mfma_f32_32x32x16_bf16 v[130:145], v[206:209], v[162:165], v[130:145]
	ds_read_b128 v[244:247], v222 offset:57344
	ds_read_b128 v[206:209], v222 offset:49152
	v_add_f32_e32 v227, v99, v227
	v_exp_f32_e32 v102, v102
	v_add_f32_e32 v227, v100, v227
	s_waitcnt lgkmcnt(3)
	v_mfma_f32_32x32x16_bf16 v[114:129], v[198:201], v[158:161], v[114:129]
	v_exp_f32_e32 v103, v103
	v_add_f32_e32 v227, v101, v227
	v_exp_f32_e32 v104, v104
	s_waitcnt lgkmcnt(2)
	v_mfma_f32_32x32x16_bf16 v[130:145], v[202:205], v[158:161], v[130:145]
	ds_read_b128 v[198:201], v223 offset:57344
	ds_read_b128 v[202:205], v223 offset:49152
	v_add_f32_e32 v227, v102, v227
	v_exp_f32_e32 v105, v105
	v_add_f32_e32 v227, v103, v227
	s_waitcnt lgkmcnt(3)
	v_mfma_f32_32x32x16_bf16 v[114:129], v[244:247], v[154:157], v[114:129]
	v_add_f32_e32 v227, v104, v227
	v_add_f32_e32 v227, v105, v227
	v_cvt_pk_bf16_f32 v74, v98, v99
	s_waitcnt lgkmcnt(2)
	v_mfma_f32_32x32x16_bf16 v[130:145], v[206:209], v[154:157], v[130:145]
	ds_read_b128 v[244:247], v224 offset:57344
	ds_read_b128 v[206:209], v224 offset:49152
	v_cvt_pk_bf16_f32 v75, v100, v101
	v_cvt_pk_bf16_f32 v76, v102, v103
	s_waitcnt lgkmcnt(3)
	v_mfma_f32_32x32x16_bf16 v[114:129], v[198:201], v[150:153], v[114:129]
	v_cvt_pk_bf16_f32 v77, v104, v105
	v_permlane32_swap_b32_e32 v74, v76
	s_waitcnt lgkmcnt(2)
	v_mfma_f32_32x32x16_bf16 v[130:145], v[202:205], v[150:153], v[130:145]
	ds_read_b64_tr_b16 v[178:179], v193 offset:0
	ds_read_b64_tr_b16 v[180:181], v193 offset:0x800
	ds_read_b64_tr_b16 v[182:183], v193 offset:0x200
	ds_read_b64_tr_b16 v[184:185], v193 offset:0xa00
	ds_read_b64_tr_b16 v[198:199], v193 offset:0x400
	ds_read_b64_tr_b16 v[200:201], v193 offset:0xc00
	ds_read_b64_tr_b16 v[202:203], v193 offset:0x600
	ds_read_b64_tr_b16 v[204:205], v193 offset:0xe00
	v_permlane32_swap_b32_e32 v75, v77
	v_add_co_u32_e32 v218, vcc, s77, v186
	s_waitcnt lgkmcnt(9)
	v_mfma_f32_32x32x16_bf16 v[114:129], v[244:247], v[146:149], v[114:129]
	s_nop 1
	v_addc_co_u32_e32 v219, vcc, 0, v187, vcc
	s_waitcnt lgkmcnt(8)
; #define SBAR() __builtin_amdgcn_sched_barrier(0)
; template <bool FIRST> __device__ __forceinline__ void partialSM(f32x16& p0, f32x16& p1, float& m_reg, float& alpha, f32x16& negm, float c_cur) {
;   float pmax = p0[0];
; #pragma unroll
;   for (int r = 1; r < 16; ++r) pmax = fmaxf(pmax, p0[r]);
; #pragma unroll
;   for (int r = 0; r < 16; ++r) pmax = fmaxf(pmax, p1[r]);
;   { auto rr = __builtin_amdgcn_permlane32_swap(__float_as_uint(pmax), __float_as_uint(pmax), false, false);
;     pmax = fmaxf(__uint_as_float(rr[0]), __uint_as_float(rr[1])); }
;   alpha = 1.f;
;   if (FIRST || !__builtin_expect(__all(pmax <= THR2), 1)) {
;     const float d = FIRST ? pmax : fmaxf(pmax, 0.f); m_reg += d; if (!FIRST) alpha = __builtin_amdgcn_exp2f(-d);
; #pragma unroll
;     for (int r = 0; r < 16; ++r) { p0[r] -= d; p1[r] -= d; }
;     const float nm = c_cur - m_reg;
; #pragma unroll
;     for (int r = 0; r < 16; ++r) negm[r] = nm;
;   }
; #pragma unroll
;   for (int r = 0; r < 16; ++r) p0[r] = __builtin_amdgcn_exp2f(p0[r]);
; }
; __device__ __forceinline__ void finishSM(f32x16& p0, f32x16& p1, float alpha, float& l_reg, bf16x8& pa0, bf16x8& pa1, bf16x8& pa2, bf16x8& pa3) {
; #pragma unroll
;   for (int r = 0; r < 16; ++r) p1[r] = __builtin_amdgcn_exp2f(p1[r]);
;   float ps = 0;
; #pragma unroll
;   for (int r = 0; r < 16; ++r) ps += p0[r];
; #pragma unroll
;   for (int r = 0; r < 16; ++r) ps += p1[r];
;   { auto rr = __builtin_amdgcn_permlane32_swap(__float_as_uint(ps), __float_as_uint(ps), false, false);
;     ps = __uint_as_float(rr[0]) + __uint_as_float(rr[1]); }
;   l_reg = l_reg * alpha + ps;
;     ...
;   PK4(p0, 0, pa0); PK4(p0, 8, pa1); PK4(p1, 0, pa2); PK4(p1, 8, pa3);
;     ...
; }
; template <int D0> __device__ __forceinline__ void pv_one(f32x16& od, int vb, bf16x8 pa0, bf16x8 pa1, bf16x8 pa2, bf16x8 pa3) {
;   const s16x4 l0 = tr_read<v_rd_off(D0, 0, 0)>(vb), h0 = tr_read<v_rd_off(D0, 0, 1)>(vb), l1 = tr_read<v_rd_off(D0, 1, 0)>(vb), h1 = tr_read<v_rd_off(D0, 1, 1)>(vb);
;   const s16x4 l2 = tr_read<v_rd_off(D0, 2, 0)>(vb), h2 = tr_read<v_rd_off(D0, 2, 1)>(vb), l3 = tr_read<v_rd_off(D0, 3, 0)>(vb), h3 = tr_read<v_rd_off(D0, 3, 1)>(vb);
;   asm volatile("s_waitcnt lgkmcnt(0)" ::: "memory"); SBAR();
;     ...
;   od = __builtin_amdgcn_mfma_f32_32x32x16_bf16(pa0, PK(l0, h0), od, 0, 0, 0);
;   od = __builtin_amdgcn_mfma_f32_32x32x16_bf16(pa1, PK(l1, h1), od, 0, 0, 0);
	v_mfma_f32_32x32x16_bf16 v[130:145], v[206:209], v[146:149], v[130:145]
	global_load_dwordx4 v[98:101], v[186:187], off offset:512
	global_load_dwordx4 v[102:105], v[186:187], off
	s_waitcnt lgkmcnt(6)
	v_mfma_f32_32x32x16_bf16 v[2:17], v[66:69], v[178:181], v[2:17]
	ds_read_b64_tr_b16 v[178:179], v193 offset:0x1000
	ds_read_b64_tr_b16 v[180:181], v193 offset:0x1800
	v_exp_f32_e32 v106, v106
	v_exp_f32_e32 v107, v107
	v_exp_f32_e32 v108, v108
	v_add_f32_e32 v227, v106, v227
	s_waitcnt lgkmcnt(6)
	v_mfma_f32_32x32x16_bf16 v[50:65], v[66:69], v[182:185], v[50:65]
	ds_read_b64_tr_b16 v[182:183], v193 offset:0x1200
	ds_read_b64_tr_b16 v[184:185], v193 offset:0x1a00
	v_exp_f32_e32 v109, v109
	v_add_f32_e32 v227, v107, v227
	v_exp_f32_e32 v110, v110
	v_add_f32_e32 v227, v108, v227
	s_waitcnt lgkmcnt(6)
	v_mfma_f32_32x32x16_bf16 v[34:49], v[66:69], v[198:201], v[34:49]
	ds_read_b64_tr_b16 v[198:199], v193 offset:0x1400
	ds_read_b64_tr_b16 v[200:201], v193 offset:0x1c00
	v_exp_f32_e32 v111, v111
	v_add_f32_e32 v227, v109, v227
	v_exp_f32_e32 v112, v112
	v_add_f32_e32 v227, v110, v227
	s_waitcnt lgkmcnt(6)
	v_mfma_f32_32x32x16_bf16 v[18:33], v[66:69], v[202:205], v[18:33]
	ds_read_b64_tr_b16 v[202:203], v193 offset:0x1600
	ds_read_b64_tr_b16 v[204:205], v193 offset:0x1e00
	v_exp_f32_e32 v113, v113
	v_add_f32_e32 v227, v111, v227
	v_add_f32_e32 v227, v112, v227
	v_add_f32_e32 v227, v113, v227
	s_waitcnt lgkmcnt(6)
	v_mfma_f32_32x32x16_bf16 v[2:17], v[70:73], v[178:181], v[2:17]
	ds_read_b64_tr_b16 v[178:179], v193 offset:0x2000
	ds_read_b64_tr_b16 v[180:181], v193 offset:0x2800
	v_mov_b32_e32 v228, v227
	v_cvt_pk_bf16_f32 v78, v106, v107
	v_cvt_pk_bf16_f32 v79, v108, v109
	v_cvt_pk_bf16_f32 v80, v110, v111
	s_waitcnt lgkmcnt(6)
	v_mfma_f32_32x32x16_bf16 v[50:65], v[70:73], v[182:185], v[50:65]
	ds_read_b64_tr_b16 v[182:183], v193 offset:0x2200
	ds_read_b64_tr_b16 v[184:185], v193 offset:0x2a00
	v_cvt_pk_bf16_f32 v81, v112, v113
	v_permlane32_swap_b32_e32 v227, v228
	v_permlane32_swap_b32_e32 v78, v80
	v_permlane32_swap_b32_e32 v79, v81
	global_load_dwordx4 v[110:113], v[218:219], off offset:512
	global_load_dwordx4 v[106:109], v[218:219], off
	s_waitcnt lgkmcnt(6)
	v_mfma_f32_32x32x16_bf16 v[34:49], v[70:73], v[198:201], v[34:49]
	ds_read_b64_tr_b16 v[198:199], v193 offset:0x2400
	ds_read_b64_tr_b16 v[200:201], v193 offset:0x2c00
	v_max_f32_e32 v218, v130, v131
	v_max3_f32 v218, v218, v132, v133
	s_waitcnt lgkmcnt(6)
	v_mfma_f32_32x32x16_bf16 v[18:33], v[70:73], v[202:205], v[18:33]
	ds_read_b64_tr_b16 v[202:203], v193 offset:0x2600
	ds_read_b64_tr_b16 v[204:205], v193 offset:0x2e00
	v_max3_f32 v218, v218, v134, v135
	v_max3_f32 v218, v218, v136, v137
	s_waitcnt lgkmcnt(6)
	v_mfma_f32_32x32x16_bf16 v[2:17], v[74:77], v[178:181], v[2:17]
	ds_read_b64_tr_b16 v[178:179], v193 offset:0x3000
	ds_read_b64_tr_b16 v[180:181], v193 offset:0x3800
	v_max3_f32 v218, v218, v138, v139
	v_max3_f32 v218, v218, v140, v141
	s_waitcnt lgkmcnt(6)
	v_mfma_f32_32x32x16_bf16 v[50:65], v[74:77], v[182:185], v[50:65]
	ds_read_b64_tr_b16 v[182:183], v193 offset:0x3200
	ds_read_b64_tr_b16 v[184:185], v193 offset:0x3a00
	v_max3_f32 v218, v218, v142, v143
	v_max3_f32 v218, v218, v144, v145
	s_waitcnt lgkmcnt(6)
	v_mfma_f32_32x32x16_bf16 v[34:49], v[74:77], v[198:201], v[34:49]
	ds_read_b64_tr_b16 v[198:199], v193 offset:0x3400
	ds_read_b64_tr_b16 v[200:201], v193 offset:0x3c00
	v_max3_f32 v218, v218, v114, v115
	v_max3_f32 v218, v218, v116, v117
	s_waitcnt lgkmcnt(6)
	v_mfma_f32_32x32x16_bf16 v[18:33], v[74:77], v[202:205], v[18:33]
	ds_read_b64_tr_b16 v[202:203], v193 offset:0x3600
	ds_read_b64_tr_b16 v[204:205], v193 offset:0x3e00
	v_max3_f32 v218, v218, v118, v119
	v_max3_f32 v218, v218, v120, v121
	s_waitcnt lgkmcnt(6)
	v_mfma_f32_32x32x16_bf16 v[2:17], v[78:81], v[178:181], v[2:17]
	v_max3_f32 v218, v218, v122, v123
	v_max3_f32 v218, v218, v124, v125
	s_waitcnt lgkmcnt(4)
	v_mfma_f32_32x32x16_bf16 v[50:65], v[78:81], v[182:185], v[50:65]
	v_max3_f32 v218, v218, v126, v127
	v_max3_f32 v218, v218, v128, v129
	s_waitcnt lgkmcnt(2)
	v_mfma_f32_32x32x16_bf16 v[34:49], v[78:81], v[198:201], v[34:49]
	v_mov_b32_e32 v219, v218
	s_waitcnt lgkmcnt(0)
	v_mfma_f32_32x32x16_bf16 v[18:33], v[78:81], v[202:205], v[18:33]
	v_permlane32_swap_b32_e32 v218, v219
	v_max_f32_e32 v66, v218, v219

; template <bool FIRST> __device__ __forceinline__ void partialSM(f32x16& p0, f32x16& p1, float& m_reg, float& alpha, f32x16& negm, float c_cur) {
;     ...
;   for (int r = 0; r < 16; ++r) p0[r] = __builtin_amdgcn_exp2f(p0[r]);
; }
; __device__ __forceinline__ void finishSM(f32x16& p0, f32x16& p1, float alpha, float& l_reg, bf16x8& pa0, bf16x8& pa1, bf16x8& pa2, bf16x8& pa3) {
; #pragma unroll
;   for (int r = 0; r < 16; ++r) p1[r] = __builtin_amdgcn_exp2f(p1[r]);
;   float ps = 0;
; #pragma unroll
;   for (int r = 0; r < 16; ++r) ps += p0[r];
; #pragma unroll
;   for (int r = 0; r < 16; ++r) ps += p1[r];
;   { auto rr = __builtin_amdgcn_permlane32_swap(__float_as_uint(ps), __float_as_uint(ps), false, false);
;     ps = __uint_as_float(rr[0]) + __uint_as_float(rr[1]); }
;   l_reg = l_reg * alpha + ps;
;     ...
;   PK4(p0, 0, pa0); PK4(p0, 8, pa1); PK4(p1, 0, pa2); PK4(p1, 8, pa3);
;     ...
; }
; template <int DQK> __device__ __forceinline__ void qkt(f32x16& p0, f32x16& p1, const char* Ks, const bf16x8* qr, int r32, int hi, const f32x16& negm) {
; #pragma unroll
;   for (int d0 = 0; d0 < DQK / 16; ++d0) { const int cb = (d0 * 16 + hi * 8) * 2;
;     const bf16x8 b0 = *reinterpret_cast<const bf16x8*>(Ks + (DQK == 128 ? KSWZ(r32, cb) : KSWZ64(r32, cb)));
;     const bf16x8 b1 = *reinterpret_cast<const bf16x8*>(Ks + (DQK == 128 ? KSWZ(32 + r32, cb) : KSWZ64(32 + r32, cb)));
;     if (d0 == 0) { p0 = __builtin_amdgcn_mfma_f32_32x32x16_bf16(b0, qr[0], negm, 0, 0, 0); p1 = __builtin_amdgcn_mfma_f32_32x32x16_bf16(b1, qr[0], negm, 0, 0, 0); }
;     else { p0 = __builtin_amdgcn_mfma_f32_32x32x16_bf16(b0, qr[d0], p0, 0, 0, 0); p1 = __builtin_amdgcn_mfma_f32_32x32x16_bf16(b1, qr[d0], p1, 0, 0, 0); } }
; }
.LBB0_76:
	s_add_i32 s14, s12, 0x80
	v_exp_f32_e32 v178, v130
	v_exp_f32_e32 v205, v131
	v_exp_f32_e32 v179, v132
	v_exp_f32_e32 v204, v133
	v_exp_f32_e32 v180, v134
	v_exp_f32_e32 v203, v135
	v_exp_f32_e32 v181, v136
	v_exp_f32_e32 v202, v137
	v_exp_f32_e32 v182, v138
	v_exp_f32_e32 v201, v139
	v_exp_f32_e32 v183, v140
	v_exp_f32_e32 v200, v141
	v_exp_f32_e32 v184, v142
	v_exp_f32_e32 v199, v143
	v_exp_f32_e32 v185, v144
	v_exp_f32_e32 v198, v145
	s_waitcnt lgkmcnt(0)
	s_barrier
	s_cmp_le_u32 s14, s16
	s_cbranch_scc0 .Lslow_g2
	ds_read_b128 v[232:235], v195 offset:40960
	ds_read_b128 v[236:239], v195 offset:32768
	ds_read_b128 v[244:247], v211 offset:40960
	ds_read_b128 v[240:243], v211 offset:32768
	v_add_f32_e32 v230, 0, v178
	v_add_f32_e32 v230, v205, v230
	v_cvt_pk_bf16_f32 v178, v178, v205
	v_add_f32_e32 v230, v179, v230
	v_add_f32_e32 v230, v204, v230
	v_cvt_pk_bf16_f32 v179, v179, v204
	v_add_f32_e32 v230, v180, v230
	v_add_f32_e32 v230, v203, v230
	v_cvt_pk_bf16_f32 v180, v180, v203
	v_add_f32_e32 v230, v181, v230
	v_add_f32_e32 v230, v202, v230
	v_cvt_pk_bf16_f32 v181, v181, v202
	s_waitcnt lgkmcnt(3)
	v_mfma_f32_32x32x16_bf16 v[98:113], v[232:235], v[174:177], v[82:97]
	v_add_f32_e32 v230, v182, v230
	v_add_f32_e32 v230, v201, v230
	v_cvt_pk_bf16_f32 v182, v182, v201
	s_waitcnt lgkmcnt(2)
	v_mfma_f32_32x32x16_bf16 v[130:145], v[236:239], v[174:177], v[82:97]
	ds_read_b128 v[232:235], v210 offset:40960
	ds_read_b128 v[236:239], v210 offset:32768
	v_add_f32_e32 v230, v183, v230
	v_add_f32_e32 v230, v200, v230
	v_cvt_pk_bf16_f32 v183, v183, v200
	s_waitcnt lgkmcnt(3)
	v_mfma_f32_32x32x16_bf16 v[98:113], v[244:247], v[170:173], v[98:113]
	v_add_f32_e32 v230, v184, v230
	v_add_f32_e32 v230, v199, v230
	v_cvt_pk_bf16_f32 v184, v184, v199
	s_waitcnt lgkmcnt(2)
	v_mfma_f32_32x32x16_bf16 v[130:145], v[240:243], v[170:173], v[130:145]
	ds_read_b128 v[244:247], v197 offset:40960
	ds_read_b128 v[240:243], v197 offset:32768
	v_add_f32_e32 v230, v185, v230
	v_add_f32_e32 v230, v198, v230
	v_cvt_pk_bf16_f32 v185, v185, v198
	s_waitcnt lgkmcnt(3)
	v_mfma_f32_32x32x16_bf16 v[98:113], v[232:235], v[166:169], v[98:113]
	v_exp_f32_e32 v114, v114
	v_exp_f32_e32 v115, v115
	v_permlane32_swap_b32_e32 v178, v180
	s_waitcnt lgkmcnt(2)
	v_mfma_f32_32x32x16_bf16 v[130:145], v[236:239], v[166:169], v[130:145]
	ds_read_b128 v[232:235], v196 offset:40960
	ds_read_b128 v[236:239], v196 offset:32768
	v_permlane32_swap_b32_e32 v179, v181
	v_permlane32_swap_b32_e32 v182, v184
	v_permlane32_swap_b32_e32 v183, v185
	s_waitcnt lgkmcnt(3)
	v_mfma_f32_32x32x16_bf16 v[98:113], v[244:247], v[162:165], v[98:113]
	v_exp_f32_e32 v116, v116
	v_add_f32_e32 v230, v114, v230
	v_exp_f32_e32 v117, v117
	s_waitcnt lgkmcnt(2)
	v_mfma_f32_32x32x16_bf16 v[130:145], v[240:243], v[162:165], v[130:145]
	ds_read_b128 v[244:247], v222 offset:40960
	ds_read_b128 v[240:243], v222 offset:32768
	v_add_f32_e32 v230, v115, v230
	v_exp_f32_e32 v118, v118
	v_add_f32_e32 v230, v116, v230
	s_waitcnt lgkmcnt(3)
	v_mfma_f32_32x32x16_bf16 v[98:113], v[232:235], v[158:161], v[98:113]
	v_exp_f32_e32 v119, v119
	v_add_f32_e32 v230, v117, v230
	v_exp_f32_e32 v120, v120
	s_waitcnt lgkmcnt(2)
	v_mfma_f32_32x32x16_bf16 v[130:145], v[236:239], v[158:161], v[130:145]
	ds_read_b128 v[232:235], v223 offset:40960
	ds_read_b128 v[236:239], v223 offset:32768
	v_add_f32_e32 v230, v118, v230
	v_exp_f32_e32 v121, v121
	v_add_f32_e32 v230, v119, v230
	s_waitcnt lgkmcnt(3)
	v_mfma_f32_32x32x16_bf16 v[98:113], v[244:247], v[154:157], v[98:113]
	v_add_f32_e32 v230, v120, v230
	v_add_f32_e32 v230, v121, v230
	v_cvt_pk_bf16_f32 v198, v114, v115
	s_waitcnt lgkmcnt(2)
	v_mfma_f32_32x32x16_bf16 v[130:145], v[240:243], v[154:157], v[130:145]
	ds_read_b128 v[244:247], v224 offset:40960
	ds_read_b128 v[240:243], v224 offset:32768
	v_cvt_pk_bf16_f32 v199, v116, v117
	v_cvt_pk_bf16_f32 v200, v118, v119
	s_waitcnt lgkmcnt(3)
	v_mfma_f32_32x32x16_bf16 v[98:113], v[232:235], v[150:153], v[98:113]
	v_cvt_pk_bf16_f32 v201, v120, v121
	v_permlane32_swap_b32_e32 v198, v200
	s_waitcnt lgkmcnt(2)
	v_mfma_f32_32x32x16_bf16 v[130:145], v[236:239], v[150:153], v[130:145]
	ds_read_b64_tr_b16 v[206:207], v190 offset:0
	ds_read_b64_tr_b16 v[208:209], v190 offset:0x800
	ds_read_b64_tr_b16 v[232:233], v190 offset:0x200
	ds_read_b64_tr_b16 v[234:235], v190 offset:0xa00
	ds_read_b64_tr_b16 v[236:237], v190 offset:0x400
	ds_read_b64_tr_b16 v[238:239], v190 offset:0xc00
	v_permlane32_swap_b32_e32 v199, v201
	v_add_co_u32_e32 v218, vcc, s80, v186
	s_waitcnt lgkmcnt(7)
	v_mfma_f32_32x32x16_bf16 v[98:113], v[244:247], v[146:149], v[98:113]
	s_nop 1
	v_addc_co_u32_e32 v219, vcc, 0, v187, vcc
	s_waitcnt lgkmcnt(6)
; template <bool FIRST> __device__ __forceinline__ void partialSM(f32x16& p0, f32x16& p1, float& m_reg, float& alpha, f32x16& negm, float c_cur) {
;   float pmax = p0[0];
; #pragma unroll
;   for (int r = 1; r < 16; ++r) pmax = fmaxf(pmax, p0[r]);
; #pragma unroll
;   for (int r = 0; r < 16; ++r) pmax = fmaxf(pmax, p1[r]);
;   { auto rr = __builtin_amdgcn_permlane32_swap(__float_as_uint(pmax), __float_as_uint(pmax), false, false);
;     pmax = fmaxf(__uint_as_float(rr[0]), __uint_as_float(rr[1])); }
;   alpha = 1.f;
;   if (FIRST || !__builtin_expect(__all(pmax <= THR2), 1)) {
;     const float d = FIRST ? pmax : fmaxf(pmax, 0.f); m_reg += d; if (!FIRST) alpha = __builtin_amdgcn_exp2f(-d);
; #pragma unroll
;     for (int r = 0; r < 16; ++r) { p0[r] -= d; p1[r] -= d; }
;     const float nm = c_cur - m_reg;
; #pragma unroll
;     for (int r = 0; r < 16; ++r) negm[r] = nm;
;   }
; #pragma unroll
;   for (int r = 0; r < 16; ++r) p0[r] = __builtin_amdgcn_exp2f(p0[r]);
; }
; __device__ __forceinline__ void finishSM(f32x16& p0, f32x16& p1, float alpha, float& l_reg, bf16x8& pa0, bf16x8& pa1, bf16x8& pa2, bf16x8& pa3) {
; #pragma unroll
;   for (int r = 0; r < 16; ++r) p1[r] = __builtin_amdgcn_exp2f(p1[r]);
;   float ps = 0;
; #pragma unroll
; template <int D0> __device__ __forceinline__ void pv_one(f32x16& od, int vb, bf16x8 pa0, bf16x8 pa1, bf16x8 pa2, bf16x8 pa3) {
;   const s16x4 l0 = tr_read<v_rd_off(D0, 0, 0)>(vb), h0 = tr_read<v_rd_off(D0, 0, 1)>(vb), l1 = tr_read<v_rd_off(D0, 1, 0)>(vb), h1 = tr_read<v_rd_off(D0, 1, 1)>(vb);
;   const s16x4 l2 = tr_read<v_rd_off(D0, 2, 0)>(vb), h2 = tr_read<v_rd_off(D0, 2, 1)>(vb), l3 = tr_read<v_rd_off(D0, 3, 0)>(vb), h3 = tr_read<v_rd_off(D0, 3, 1)>(vb);
;   asm volatile("s_waitcnt lgkmcnt(0)" ::: "memory"); SBAR();
;     ...
;   od = __builtin_amdgcn_mfma_f32_32x32x16_bf16(pa0, PK(l0, h0), od, 0, 0, 0);
;   od = __builtin_amdgcn_mfma_f32_32x32x16_bf16(pa1, PK(l1, h1), od, 0, 0, 0);
;   od = __builtin_amdgcn_mfma_f32_32x32x16_bf16(pa2, PK(l2, h2), od, 0, 0, 0);
;   od = __builtin_amdgcn_mfma_f32_32x32x16_bf16(pa3, PK(l3, h3), od, 0, 0, 0);
;     ...
; }
; __device__ __forceinline__ void pv_d0(f32x16* o, int vb, bf16x8 pa0, bf16x8 pa1, bf16x8 pa2, bf16x8 pa3) {
;   pv_one<0>(o[0], vb, pa0, pa1, pa2, pa3); pv_one<1>(o[1], vb, pa0, pa1, pa2, pa3); pv_one<2>(o[2], vb, pa0, pa1, pa2, pa3); pv_one<3>(o[3], vb, pa0, pa1, pa2, pa3);
	v_mfma_f32_32x32x16_bf16 v[130:145], v[240:243], v[146:149], v[130:145]
	ds_read_b64_tr_b16 v[240:241], v190 offset:0x600
	ds_read_b64_tr_b16 v[242:243], v190 offset:0xe00
	global_load_dwordx4 v[114:117], v[218:219], off offset:512
	global_load_dwordx4 v[118:121], v[218:219], off
	s_waitcnt lgkmcnt(6)
	v_mfma_f32_32x32x16_bf16 v[2:17], v[178:181], v[206:209], v[2:17]
	ds_read_b64_tr_b16 v[206:207], v190 offset:0x1000
	ds_read_b64_tr_b16 v[208:209], v190 offset:0x1800
	v_exp_f32_e32 v122, v122
	v_exp_f32_e32 v123, v123
	v_exp_f32_e32 v124, v124
	v_add_f32_e32 v230, v122, v230
	s_waitcnt lgkmcnt(6)
	v_mfma_f32_32x32x16_bf16 v[50:65], v[178:181], v[232:235], v[50:65]
	ds_read_b64_tr_b16 v[232:233], v190 offset:0x1200
	ds_read_b64_tr_b16 v[234:235], v190 offset:0x1a00
	v_exp_f32_e32 v125, v125
	v_add_f32_e32 v230, v123, v230
	v_exp_f32_e32 v126, v126
	v_add_f32_e32 v230, v124, v230
	s_waitcnt lgkmcnt(6)
	v_mfma_f32_32x32x16_bf16 v[34:49], v[178:181], v[236:239], v[34:49]
	ds_read_b64_tr_b16 v[236:237], v190 offset:0x1400
	ds_read_b64_tr_b16 v[238:239], v190 offset:0x1c00
	v_exp_f32_e32 v127, v127
	v_add_f32_e32 v230, v125, v230
	v_exp_f32_e32 v128, v128
	v_add_f32_e32 v230, v126, v230
	s_waitcnt lgkmcnt(6)
	v_mfma_f32_32x32x16_bf16 v[18:33], v[178:181], v[240:243], v[18:33]
	ds_read_b64_tr_b16 v[240:241], v190 offset:0x1600
	ds_read_b64_tr_b16 v[242:243], v190 offset:0x1e00
	v_exp_f32_e32 v129, v129
	v_add_f32_e32 v230, v127, v230
	v_add_f32_e32 v230, v128, v230
	v_add_f32_e32 v230, v129, v230
	s_waitcnt lgkmcnt(6)
	v_mfma_f32_32x32x16_bf16 v[2:17], v[182:185], v[206:209], v[2:17]
	ds_read_b64_tr_b16 v[206:207], v190 offset:0x2000
	ds_read_b64_tr_b16 v[208:209], v190 offset:0x2800
	v_mov_b32_e32 v231, v230
	v_cvt_pk_bf16_f32 v202, v122, v123
	v_cvt_pk_bf16_f32 v203, v124, v125
	v_cvt_pk_bf16_f32 v204, v126, v127
	s_waitcnt lgkmcnt(6)
	v_mfma_f32_32x32x16_bf16 v[50:65], v[182:185], v[232:235], v[50:65]
	ds_read_b64_tr_b16 v[232:233], v190 offset:0x2200
	ds_read_b64_tr_b16 v[234:235], v190 offset:0x2a00
	v_cvt_pk_bf16_f32 v205, v128, v129
	v_permlane32_swap_b32_e32 v230, v231
	v_permlane32_swap_b32_e32 v202, v204
	v_permlane32_swap_b32_e32 v203, v205
	v_add_co_u32_e32 v218, vcc, s81, v186
	s_nop 1
	v_addc_co_u32_e32 v219, vcc, 0, v187, vcc
	global_load_dwordx4 v[126:129], v[218:219], off offset:512
	global_load_dwordx4 v[122:125], v[218:219], off
	s_waitcnt lgkmcnt(6)
	v_mfma_f32_32x32x16_bf16 v[34:49], v[182:185], v[236:239], v[34:49]
	ds_read_b64_tr_b16 v[236:237], v190 offset:0x2400
	ds_read_b64_tr_b16 v[238:239], v190 offset:0x2c00
	v_max_f32_e32 v218, v130, v131
	v_max3_f32 v218, v218, v132, v133
	s_waitcnt lgkmcnt(6)
	v_mfma_f32_32x32x16_bf16 v[18:33], v[182:185], v[240:243], v[18:33]
	ds_read_b64_tr_b16 v[240:241], v190 offset:0x2600
	ds_read_b64_tr_b16 v[242:243], v190 offset:0x2e00
	v_max3_f32 v218, v218, v134, v135
	v_max3_f32 v218, v218, v136, v137
	s_waitcnt lgkmcnt(6)
	v_mfma_f32_32x32x16_bf16 v[2:17], v[198:201], v[206:209], v[2:17]
	ds_read_b64_tr_b16 v[206:207], v190 offset:0x3000
	ds_read_b64_tr_b16 v[208:209], v190 offset:0x3800
	v_max3_f32 v218, v218, v138, v139
	v_max3_f32 v218, v218, v140, v141
	s_waitcnt lgkmcnt(6)
	v_mfma_f32_32x32x16_bf16 v[50:65], v[198:201], v[232:235], v[50:65]
	ds_read_b64_tr_b16 v[232:233], v190 offset:0x3200
	ds_read_b64_tr_b16 v[234:235], v190 offset:0x3a00
	v_max3_f32 v218, v218, v142, v143
	v_max3_f32 v218, v218, v144, v145
	s_waitcnt lgkmcnt(6)
	v_mfma_f32_32x32x16_bf16 v[34:49], v[198:201], v[236:239], v[34:49]
	ds_read_b64_tr_b16 v[236:237], v190 offset:0x3400
	ds_read_b64_tr_b16 v[238:239], v190 offset:0x3c00
	v_max3_f32 v218, v218, v98, v99
	v_max3_f32 v218, v218, v100, v101
	s_waitcnt lgkmcnt(6)
	v_mfma_f32_32x32x16_bf16 v[18:33], v[198:201], v[240:243], v[18:33]
	ds_read_b64_tr_b16 v[240:241], v190 offset:0x3600
	ds_read_b64_tr_b16 v[242:243], v190 offset:0x3e00
	v_max3_f32 v218, v218, v102, v103
	v_max3_f32 v218, v218, v104, v105
	s_waitcnt lgkmcnt(6)
	v_mfma_f32_32x32x16_bf16 v[2:17], v[202:205], v[206:209], v[2:17]
	v_max3_f32 v218, v218, v106, v107
	v_max3_f32 v218, v218, v108, v109
	s_waitcnt lgkmcnt(4)
	v_mfma_f32_32x32x16_bf16 v[50:65], v[202:205], v[232:235], v[50:65]
	v_max3_f32 v218, v218, v110, v111
	v_max3_f32 v218, v218, v112, v113
	s_waitcnt lgkmcnt(2)
	v_mfma_f32_32x32x16_bf16 v[34:49], v[202:205], v[236:239], v[34:49]
	v_mov_b32_e32 v219, v218
	s_waitcnt lgkmcnt(0)
	v_mfma_f32_32x32x16_bf16 v[18:33], v[202:205], v[240:243], v[18:33]
	v_permlane32_swap_b32_e32 v218, v219
	v_max_f32_e32 v179, v218, v219
